# v055 plus: per-tile bias constant selected with s_cselect from two SGPR copies instead of s_cselect_b64 vcc + v_cndmask (both NEGM checks)
# baseline (speedup 1.0000x reference)
; __device__ __forceinline__ void scoreConst(f32x16& p0, f32x16& p1, float& m_reg, float& alpha) {
;     ...
;   for (int r = 0; r < 16; ++r) p0[r] = __builtin_amdgcn_exp2f(p0[r]);
; template <int MODE>
; __device__ __forceinline__ void attn_unit(bf16r* P0, const bf16r* __restrict__ PKV, int rowbase, int seqL, int h, int blk, float lam,
;                                           const float* __restrict__ subg, const float* __restrict__ tsrc, char* lds) {
;     ...
;     { const float nv_ = CB(0) - m_reg; _Pragma("unroll") for (int r = 0; r < 16; ++r) negm[r] = nv_; asm volatile("" : "+v"(negm)); }
;     qkt0(pA0, pA1, lds + SLOT_K, Qs, r32, hi, kcolB, negm); scoreConst(pA0, pA1, m_reg, alA);
;     int sPrev = 0, sCur = SLOT, sNext = 2 * SLOT;
;     ...
;     for (int j = 1; j + 1 < NH; j += 2) {
;       STEP(pB0, pB1, mnB, alB, pA0, pA1, alA, j);
.LBB0_211:
	v_exp_f32_e32 v161, v112
	v_exp_f32_e32 v163, v113
	v_exp_f32_e32 v159, v114
	v_exp_f32_e32 v162, v115
	v_exp_f32_e32 v157, v116
	v_exp_f32_e32 v160, v117
	v_exp_f32_e32 v156, v118
	v_exp_f32_e32 v158, v119
	v_exp_f32_e32 v153, v120
	v_exp_f32_e32 v155, v121
	v_exp_f32_e32 v151, v122
	v_exp_f32_e32 v154, v123
	v_exp_f32_e32 v149, v124
	v_exp_f32_e32 v152, v125
	v_exp_f32_e32 v148, v126
	v_exp_f32_e32 v150, v127
	s_sub_i32 s38, s58, s57
	s_cmp_lt_i32 s38, 3
	s_cbranch_scc1 .LBB0_231
	v_lshl_or_b32 v252, v182, 12, v168
	v_lshl_or_b32 v253, v188, 12, v168
	v_readfirstlane_b32 s100, v14
	v_readfirstlane_b32 s101, v15
	s_add_i32 s39, s38, -1
	v_cmp_gt_u32_e64 s[4:5], 32, v169
	s_mov_b32 s58, 2
	s_mov_b32 s37, 0x10000
	s_mov_b32 s36, 0x8000
	s_mov_b32 s34, 0
.LBB0_213:
	s_mov_b32 s59, s36
	s_mov_b32 s36, s34
	s_add_i32 s34, s58, -1
	s_cmp_lt_u32 s34, s56
	s_cselect_b32 s98, s100, s101
	v_sub_f32_e32 v112, s98, v192
	v_cmp_neq_f32_e32 vcc, v112, v80
	s_cbranch_vccz .LBB0_215
	v_mov_b32_e32 v113, v112
	v_mov_b32_e32 v114, v112
	v_mov_b32_e32 v115, v112
	v_mov_b32_e32 v116, v112
	v_mov_b32_e32 v117, v112
	v_mov_b32_e32 v118, v112
	v_mov_b32_e32 v119, v112
	v_mov_b32_e32 v120, v112
	v_mov_b32_e32 v121, v112
	v_mov_b32_e32 v122, v112
	v_mov_b32_e32 v123, v112
	v_mov_b32_e32 v124, v112
	v_mov_b32_e32 v125, v112
	v_mov_b32_e32 v126, v112
	v_mov_b32_e32 v127, v112
	s_nop 0
	v_mov_b64_e32 v[80:81], v[112:113]
	v_mov_b64_e32 v[82:83], v[114:115]
	v_mov_b64_e32 v[84:85], v[116:117]
	v_mov_b64_e32 v[86:87], v[118:119]
	v_mov_b64_e32 v[88:89], v[120:121]
	v_mov_b64_e32 v[90:91], v[122:123]
	v_mov_b64_e32 v[92:93], v[124:125]
	v_mov_b64_e32 v[94:95], v[126:127]

; template <int MODE>
; __device__ __forceinline__ void attn_unit(bf16r* P0, const bf16r* __restrict__ PKV, int rowbase, int seqL, int h, int blk, float lam,
;                                           const float* __restrict__ subg, const float* __restrict__ tsrc, char* lds) {
;     ...
;     for (int j = 1; j + 1 < NH; j += 2) {
;       STEP(pB0, pB1, mnB, alB, pA0, pA1, alA, j);
;       STEP(pA0, pA1, mnA, alA, pB0, pB1, alB, j + 1);
.LBB0_220:
	s_cmp_lt_u32 s58, s56
	s_cselect_b32 s98, s100, s101
	v_sub_f32_e32 v96, s98, v192
	v_cmp_neq_f32_e32 vcc, v96, v80
	s_waitcnt lgkmcnt(0)
	s_barrier
	s_cbranch_vccz .LBB0_222
	v_mov_b32_e32 v97, v96
	v_mov_b32_e32 v98, v96
	v_mov_b32_e32 v99, v96
	v_mov_b32_e32 v100, v96
	v_mov_b32_e32 v101, v96
	v_mov_b32_e32 v102, v96
	v_mov_b32_e32 v103, v96
	v_mov_b32_e32 v104, v96
	v_mov_b32_e32 v105, v96
	v_mov_b32_e32 v106, v96
	v_mov_b32_e32 v107, v96
	v_mov_b32_e32 v108, v96
	v_mov_b32_e32 v109, v96
	v_mov_b32_e32 v110, v96
	v_mov_b32_e32 v111, v96
	s_nop 0
	v_mov_b64_e32 v[80:81], v[96:97]
	v_mov_b64_e32 v[82:83], v[98:99]
	v_mov_b64_e32 v[84:85], v[100:101]
	v_mov_b64_e32 v[86:87], v[102:103]
	v_mov_b64_e32 v[88:89], v[104:105]
	v_mov_b64_e32 v[90:91], v[106:107]
	v_mov_b64_e32 v[92:93], v[108:109]
	v_mov_b64_e32 v[94:95], v[110:111]
